# MLA attention loop: V-fragment reads hoisted/batched with counted lgkmcnt; bpermute max-reduce -> permlane swaps
# speedup vs baseline: 1.0991x; 1.0082x over previous
.LBB0_290:
	ds_read_b128 v[248:251], v136 offset:35840
	ds_read_b128 v[252:255], v136 offset:35904
	v_exp_f32_e32 v131, v116
	v_exp_f32_e32 v130, v104
	v_exp_f32_e32 v133, v117
	v_exp_f32_e32 v132, v105
	v_exp_f32_e32 v135, v118
	v_exp_f32_e32 v134, v106
	v_exp_f32_e32 v217, v119
	v_exp_f32_e32 v216, v107
	v_exp_f32_e32 v219, v120
	v_exp_f32_e32 v218, v112
	v_pk_add_f32 v[104:105], v[130:131], 0 op_sel_hi:[1,0]
	v_exp_f32_e32 v121, v121
	v_exp_f32_e32 v120, v113
	v_pk_add_f32 v[104:105], v[132:133], v[104:105]
	v_exp_f32_e32 v221, v122
	v_exp_f32_e32 v220, v114
	v_pk_add_f32 v[104:105], v[134:135], v[104:105]
	v_exp_f32_e32 v123, v123
	v_exp_f32_e32 v122, v115
	v_pk_add_f32 v[104:105], v[216:217], v[104:105]
	v_exp_f32_e32 v223, v124
	v_exp_f32_e32 v222, v108
	v_pk_add_f32 v[104:105], v[218:219], v[104:105]
	v_exp_f32_e32 v125, v125
	v_exp_f32_e32 v124, v109
	v_pk_add_f32 v[104:105], v[120:121], v[104:105]
	v_exp_f32_e32 v225, v126
	v_pk_add_f32 v[104:105], v[220:221], v[104:105]
	v_exp_f32_e32 v224, v110
	v_exp_f32_e32 v127, v127
	v_pk_add_f32 v[104:105], v[122:123], v[104:105]
	v_exp_f32_e32 v126, v111
	v_exp_f32_e32 v227, v100
	v_pk_add_f32 v[104:105], v[222:223], v[104:105]
	v_exp_f32_e32 v226, v96
	v_exp_f32_e32 v229, v101
	v_pk_add_f32 v[104:105], v[124:125], v[104:105]
	v_exp_f32_e32 v228, v97
	v_exp_f32_e32 v231, v102
	v_exp_f32_e32 v230, v98
	v_pk_add_f32 v[96:97], v[224:225], v[104:105]
	v_exp_f32_e32 v233, v103
	v_exp_f32_e32 v232, v99
	v_pk_add_f32 v[96:97], v[126:127], v[96:97]
	v_cvt_pk_bf16_f32 v100, v131, v133
	v_pk_add_f32 v[96:97], v[226:227], v[96:97]
	v_cvt_pk_bf16_f32 v101, v135, v217
	v_pk_add_f32 v[96:97], v[228:229], v[96:97]
	v_cvt_pk_bf16_f32 v102, v219, v121
	v_pk_add_f32 v[96:97], v[230:231], v[96:97]
	v_cvt_pk_bf16_f32 v103, v221, v123
	v_pk_add_f32 v[96:97], v[232:233], v[96:97]
	v_cvt_pk_bf16_f32 v116, v223, v125
	v_pk_add_f32 v[166:167], v[96:97], v[128:129]
	v_cvt_pk_bf16_f32 v117, v225, v127
	v_cvt_pk_bf16_f32 v118, v227, v229
	v_cvt_pk_bf16_f32 v119, v231, v233
	v_cvt_pk_bf16_f32 v96, v130, v132
	v_cvt_pk_bf16_f32 v97, v134, v216
	v_cvt_pk_bf16_f32 v98, v218, v120
	v_cvt_pk_bf16_f32 v99, v220, v122
	v_cvt_pk_bf16_f32 v104, v222, v124
	v_cvt_pk_bf16_f32 v105, v224, v126
	v_cvt_pk_bf16_f32 v106, v226, v228
	v_cvt_pk_bf16_f32 v107, v230, v232
	s_setprio 1
	ds_read_b128 v[216:219], v136 offset:38144
	ds_read_b128 v[220:223], v136 offset:38208
	ds_read_b128 v[224:227], v136 offset:40448
	ds_read_b128 v[228:231], v136 offset:40512
	ds_read_b128 v[120:123], v136 offset:42752
	ds_read_b128 v[124:127], v136 offset:42816
	s_waitcnt lgkmcnt(6)
	v_mfma_f32_16x16x32_bf16 v[76:79], v[248:251], v[100:103], v[76:79]
	v_mfma_f32_16x16x32_bf16 v[108:111], v[248:251], v[96:99], v[92:95]
	s_waitcnt lgkmcnt(6)
	v_mfma_f32_16x16x32_bf16 v[92:95], v[252:255], v[116:119], v[76:79]
	v_mfma_f32_16x16x32_bf16 v[76:79], v[252:255], v[104:107], v[108:111]
	s_waitcnt lgkmcnt(5)
	v_mfma_f32_16x16x32_bf16 v[88:91], v[216:219], v[100:103], v[88:91]
	v_mfma_f32_16x16x32_bf16 v[72:75], v[216:219], v[96:99], v[72:75]
	s_waitcnt lgkmcnt(4)
	v_mfma_f32_16x16x32_bf16 v[88:91], v[220:223], v[116:119], v[88:91]
	v_mfma_f32_16x16x32_bf16 v[72:75], v[220:223], v[104:107], v[72:75]
	s_waitcnt lgkmcnt(3)
	v_mfma_f32_16x16x32_bf16 v[84:87], v[224:227], v[100:103], v[84:87]
	v_mfma_f32_16x16x32_bf16 v[68:71], v[224:227], v[96:99], v[68:71]
	s_waitcnt lgkmcnt(2)
	v_mfma_f32_16x16x32_bf16 v[84:87], v[228:231], v[116:119], v[84:87]
	v_mfma_f32_16x16x32_bf16 v[68:71], v[228:231], v[104:107], v[68:71]
	s_waitcnt lgkmcnt(1)
	v_mfma_f32_16x16x32_bf16 v[64:67], v[120:123], v[96:99], v[64:67]
	v_mfma_f32_16x16x32_bf16 v[80:83], v[120:123], v[100:103], v[80:83]
	s_waitcnt lgkmcnt(0)
	v_mfma_f32_16x16x32_bf16 v[80:83], v[124:127], v[116:119], v[80:83]
	v_mfma_f32_16x16x32_bf16 v[64:67], v[124:127], v[104:107], v[64:67]
	s_setprio 0
	s_add_i32 s1, s1, 2
	s_cmp_lt_u32 s5, s0
	s_waitcnt vmcnt(8)
	ds_write_b128 v208, v[44:47]
	s_waitcnt vmcnt(7)
	ds_write_b128 v209, v[48:51]
	ds_write_b128 v210, v[56:59]
	s_waitcnt vmcnt(6)
	ds_write_b64 v211, v[60:61] offset:13312
	ds_write_b64 v212, v[62:63] offset:13312
	s_waitcnt vmcnt(5)
	ds_write_b64 v213, v[52:53] offset:13312
	ds_write_b64 v214, v[54:55] offset:13312
	s_waitcnt lgkmcnt(0)
	s_barrier
	s_cbranch_scc0 .LBB0_298
.LBB0_291:
	s_add_i32 s5, s1, -1
	s_min_i32 s6, s5, s4
	s_lshl_b32 s7, s6, 6
	s_add_i32 s7, s7, s16
	v_add_u32_e32 v52, s7, v205
	v_add_u32_e32 v44, s7, v203
	v_add_u32_e32 v48, s7, v204
	v_ashrrev_i32_e32 v53, 31, v52
	v_ashrrev_i32_e32 v45, 31, v44
	s_movk_i32 s18, 0xff80
	v_ashrrev_i32_e32 v49, 31, v48
	v_lshlrev_b64 v[54:55], 9, v[52:53]
	v_lshlrev_b64 v[52:53], 6, v[52:53]
	v_lshlrev_b64 v[46:47], 9, v[44:45]
	v_lshlrev_b64 v[44:45], 6, v[44:45]
	s_mov_b32 s19, -1
	v_lshlrev_b64 v[50:51], 9, v[48:49]
	v_lshlrev_b64 v[48:49], 6, v[48:49]
	v_lshl_add_u64 v[52:53], v[160:161], 0, v[52:53]
	v_lshl_add_u64 v[44:45], v[152:153], 0, v[44:45]
	v_lshl_add_u64 v[48:49], v[156:157], 0, v[48:49]
	v_lshl_add_u64 v[54:55], v[162:163], 0, v[54:55]
	v_lshl_add_u64 v[52:53], v[52:53], 0, s[18:19]
	v_lshl_add_u64 v[46:47], v[154:155], 0, v[46:47]
	v_lshl_add_u64 v[44:45], v[44:45], 0, s[18:19]
	v_lshl_add_u64 v[50:51], v[158:159], 0, v[50:51]
	v_lshl_add_u64 v[48:49], v[48:49], 0, s[18:19]
	v_cndmask_b32_e64 v53, v53, v55, s[42:43]
	v_cndmask_b32_e64 v52, v52, v54, s[42:43]
	s_lshl_b32 s94, s6, 7
	v_cndmask_b32_e64 v45, v45, v47, s[38:39]
	v_cndmask_b32_e64 v44, v44, v46, s[38:39]
	v_cndmask_b32_e64 v49, v49, v51, s[40:41]
	v_cndmask_b32_e64 v48, v48, v50, s[40:41]
	global_load_dwordx4 v[56:59], v[52:53], off
	v_lshl_add_u64 v[52:53], v[146:147], 0, s[94:95]
	v_lshl_add_u64 v[54:55], v[148:149], 0, s[94:95]
	global_load_dwordx4 v[44:47], v[44:45], off
	s_nop 0
	global_load_dwordx4 v[48:51], v[48:49], off
	s_nop 0
	global_load_dwordx4 v[60:63], v[52:53], off
	s_nop 0
	global_load_dwordx4 v[52:55], v[54:55], off
	s_setprio 1
	ds_read_b128 v[104:107], v151
	ds_read_b128 v[112:115], v151 offset:64
	v_xor_b32_e32 v96, 0x80000000, v165
	v_pk_add_f32 v[100:101], v[164:165], 0 neg_lo:[1,1] neg_hi:[1,1]
	v_mov_b32_e32 v97, v96
	v_mov_b32_e32 v98, v96
	v_mov_b32_e32 v99, v96
	v_mov_b32_e32 v101, v100
	v_mov_b32_e32 v102, v100
	v_mov_b32_e32 v103, v100
	s_waitcnt lgkmcnt(1)
	v_mfma_f32_16x16x32_bf16 v[108:111], v[104:107], v[8:11], v[96:99]
	ds_read_b128 v[120:123], v151 offset:3392
	ds_read_b128 v[128:131], v151 offset:6720
	ds_read_b128 v[132:135], v151 offset:6784
	v_mfma_f32_16x16x32_bf16 v[104:107], v[104:107], v[20:23], v[100:103]
	ds_read_b128 v[216:219], v151 offset:10048
	s_waitcnt lgkmcnt(4)
	v_mfma_f32_16x16x32_bf16 v[108:111], v[112:115], v[12:15], v[108:111]
	v_mfma_f32_16x16x32_bf16 v[104:107], v[112:115], v[24:27], v[104:107]
	ds_read_b128 v[112:115], v151 offset:128
	s_waitcnt lgkmcnt(0)
	v_mfma_f32_16x16x32_bf16 v[116:119], v[112:115], v[16:19], v[108:111]
	s_nop 3
	ds_read_b128 v[108:111], v151 offset:3328
	v_mfma_f32_16x16x32_bf16 v[104:107], v[112:115], v[28:31], v[104:107]
	s_waitcnt lgkmcnt(0)
	v_mfma_f32_16x16x32_bf16 v[112:115], v[108:111], v[8:11], v[96:99]
	v_mfma_f32_16x16x32_bf16 v[108:111], v[108:111], v[20:23], v[100:103]
	v_mfma_f32_16x16x32_bf16 v[112:115], v[120:123], v[12:15], v[112:115]
	v_mfma_f32_16x16x32_bf16 v[108:111], v[120:123], v[24:27], v[108:111]
	ds_read_b128 v[120:123], v151 offset:3456
	s_waitcnt lgkmcnt(0)
	v_mfma_f32_16x16x32_bf16 v[124:127], v[120:123], v[16:19], v[112:115]
	s_nop 3
	ds_read_b128 v[112:115], v151 offset:6656
	v_mfma_f32_16x16x32_bf16 v[108:111], v[120:123], v[28:31], v[108:111]
	s_waitcnt lgkmcnt(0)
	v_mfma_f32_16x16x32_bf16 v[120:123], v[112:115], v[8:11], v[96:99]
	v_mfma_f32_16x16x32_bf16 v[112:115], v[112:115], v[20:23], v[100:103]
	v_mfma_f32_16x16x32_bf16 v[120:123], v[128:131], v[12:15], v[120:123]
	v_mfma_f32_16x16x32_bf16 v[112:115], v[128:131], v[24:27], v[112:115]
	v_mfma_f32_16x16x32_bf16 v[128:131], v[132:135], v[16:19], v[120:123]
	s_nop 5
	ds_read_b128 v[120:123], v151 offset:9984
	v_mfma_f32_16x16x32_bf16 v[112:115], v[132:135], v[28:31], v[112:115]
	s_waitcnt lgkmcnt(0)
	v_mfma_f32_16x16x32_bf16 v[132:135], v[120:123], v[8:11], v[96:99]
	v_mfma_f32_16x16x32_bf16 v[120:123], v[120:123], v[20:23], v[100:103]
	v_mfma_f32_16x16x32_bf16 v[132:135], v[216:219], v[12:15], v[132:135]
	v_mfma_f32_16x16x32_bf16 v[120:123], v[216:219], v[24:27], v[120:123]
	ds_read_b128 v[216:219], v151 offset:10112
	s_waitcnt lgkmcnt(0)
	v_mfma_f32_16x16x32_bf16 v[132:135], v[216:219], v[16:19], v[132:135]
	v_mfma_f32_16x16x32_bf16 v[120:123], v[216:219], v[28:31], v[120:123]
	s_setprio 0
	v_max_f32_e32 v97, v117, v117
	v_max_f32_e32 v98, v116, v116
	v_max_f32_e32 v97, v98, v97
	v_max_f32_e32 v98, v119, v119
	v_max_f32_e32 v99, v118, v118
	v_max_f32_e32 v98, v99, v98
	v_max_f32_e32 v99, v127, v127
	v_max_f32_e32 v101, v126, v126
	v_max_f32_e32 v99, v101, v99
	v_max3_f32 v99, v124, v125, v99
	v_max3_f32 v97, v97, v98, v99
	v_max_f32_e32 v98, v131, v131
	v_max_f32_e32 v99, v130, v130
	v_max_f32_e32 v98, v99, v98
	v_max_f32_e32 v99, v135, v135
	v_max_f32_e32 v101, v134, v134
	v_max_f32_e32 v99, v101, v99
	v_max3_f32 v98, v128, v129, v98
	v_max3_f32 v99, v132, v133, v99
	v_max3_f32 v97, v97, v98, v99
	v_mov_b32_e32 v98, v97
	v_max_f32_e32 v99, v104, v104
	v_max_f32_e32 v101, v106, v106
	v_max_f32_e32 v102, v110, v110
	s_mov_b32 s6, 0x41000000
	s_nop 1
	v_permlane16_swap_b32_e32 v98, v97
	v_max_f32_e32 v97, v97, v98
	v_mov_b32_e32 v98, v97
	s_nop 1
	v_permlane32_swap_b32_e32 v98, v97
	v_max_f32_e32 v97, v97, v98
	v_max_f32_e32 v98, v105, v105
	v_max_f32_e32 v98, v99, v98
	v_max_f32_e32 v99, v107, v107
	v_max_f32_e32 v99, v101, v99
	v_max_f32_e32 v101, v111, v111
	v_max_f32_e32 v101, v102, v101
	v_max3_f32 v101, v108, v109, v101
	v_max3_f32 v98, v98, v99, v101
	v_max_f32_e32 v99, v115, v115
	v_max_f32_e32 v101, v114, v114
	v_max_f32_e32 v99, v101, v99
	v_max_f32_e32 v101, v123, v123
	v_max_f32_e32 v102, v122, v122
	v_max_f32_e32 v101, v102, v101
	v_max3_f32 v99, v112, v113, v99
	v_max3_f32 v101, v120, v121, v101
	v_max3_f32 v98, v98, v99, v101
	v_mov_b32_e32 v99, v98
	s_nop 1
	v_permlane16_swap_b32_e32 v99, v98
	v_max_f32_e32 v98, v98, v99
	v_mov_b32_e32 v99, v98
	s_nop 1
	v_permlane32_swap_b32_e32 v99, v98
	v_max_f32_e32 v98, v98, v99
	v_max_f32_e32 v99, v97, v98
	v_cmp_lt_f32_e32 vcc, s6, v99
	s_cbranch_vccz .LBB0_293
	v_max_f32_e32 v96, v97, v97
	v_max_f32_e32 v96, 0, v96
	v_pk_add_f32 v[116:117], v[116:117], v[96:97] op_sel_hi:[1,0] neg_lo:[0,1] neg_hi:[0,1]
	v_pk_add_f32 v[118:119], v[118:119], v[96:97] op_sel_hi:[1,0] neg_lo:[0,1] neg_hi:[0,1]
	v_pk_add_f32 v[124:125], v[124:125], v[96:97] op_sel_hi:[1,0] neg_lo:[0,1] neg_hi:[0,1]
	v_pk_add_f32 v[126:127], v[126:127], v[96:97] op_sel_hi:[1,0] neg_lo:[0,1] neg_hi:[0,1]
	v_pk_add_f32 v[128:129], v[128:129], v[96:97] op_sel_hi:[1,0] neg_lo:[0,1] neg_hi:[0,1]
	v_pk_add_f32 v[130:131], v[130:131], v[96:97] op_sel_hi:[1,0] neg_lo:[0,1] neg_hi:[0,1]
	v_pk_add_f32 v[132:133], v[132:133], v[96:97] op_sel_hi:[1,0] neg_lo:[0,1] neg_hi:[0,1]
	v_pk_add_f32 v[134:135], v[134:135], v[96:97] op_sel_hi:[1,0] neg_lo:[0,1] neg_hi:[0,1]
	v_max_f32_e32 v97, v98, v98
	v_exp_f32_e64 v100, -v96
	v_max_f32_e32 v98, 0, v97
	v_exp_f32_e64 v102, -v98
	v_mov_b32_e32 v99, v96
	v_pk_add_f32 v[164:165], v[164:165], v[98:99]
	v_mov_b32_e32 v103, v100
	v_pk_mul_f32 v[94:95], v[94:95], v[100:101] op_sel_hi:[1,0]
	v_pk_mul_f32 v[92:93], v[92:93], v[100:101] op_sel_hi:[1,0]
	v_pk_mul_f32 v[90:91], v[90:91], v[100:101] op_sel_hi:[1,0]
	v_pk_mul_f32 v[88:89], v[88:89], v[100:101] op_sel_hi:[1,0]
	v_pk_mul_f32 v[86:87], v[86:87], v[100:101] op_sel_hi:[1,0]
	v_pk_mul_f32 v[84:85], v[84:85], v[100:101] op_sel_hi:[1,0]
	v_pk_mul_f32 v[82:83], v[82:83], v[100:101] op_sel_hi:[1,0]
	v_pk_mul_f32 v[80:81], v[80:81], v[100:101] op_sel_hi:[1,0]
	v_pk_mul_f32 v[166:167], v[166:167], v[102:103]
	v_pk_mul_f32 v[78:79], v[78:79], v[102:103] op_sel_hi:[1,0]
	v_pk_mul_f32 v[76:77], v[76:77], v[102:103] op_sel_hi:[1,0]
	v_pk_mul_f32 v[74:75], v[74:75], v[102:103] op_sel_hi:[1,0]
	v_pk_mul_f32 v[72:73], v[72:73], v[102:103] op_sel_hi:[1,0]
	v_pk_mul_f32 v[70:71], v[70:71], v[102:103] op_sel_hi:[1,0]
	v_pk_mul_f32 v[68:69], v[68:69], v[102:103] op_sel_hi:[1,0]
	v_pk_mul_f32 v[66:67], v[66:67], v[102:103] op_sel_hi:[1,0]
	v_pk_mul_f32 v[64:65], v[64:65], v[102:103] op_sel_hi:[1,0]
	v_pk_add_f32 v[104:105], v[104:105], v[98:99] op_sel_hi:[1,0] neg_lo:[0,1] neg_hi:[0,1]
	v_pk_add_f32 v[106:107], v[106:107], v[98:99] op_sel_hi:[1,0] neg_lo:[0,1] neg_hi:[0,1]
	v_pk_add_f32 v[108:109], v[108:109], v[98:99] op_sel_hi:[1,0] neg_lo:[0,1] neg_hi:[0,1]
	v_pk_add_f32 v[110:111], v[110:111], v[98:99] op_sel_hi:[1,0] neg_lo:[0,1] neg_hi:[0,1]
	v_pk_add_f32 v[112:113], v[112:113], v[98:99] op_sel_hi:[1,0] neg_lo:[0,1] neg_hi:[0,1]
	v_pk_add_f32 v[114:115], v[114:115], v[98:99] op_sel_hi:[1,0] neg_lo:[0,1] neg_hi:[0,1]
	v_pk_add_f32 v[120:121], v[120:121], v[98:99] op_sel_hi:[1,0] neg_lo:[0,1] neg_hi:[0,1]
	v_pk_add_f32 v[122:123], v[122:123], v[98:99] op_sel_hi:[1,0] neg_lo:[0,1] neg_hi:[0,1]
	v_xor_b32_e32 v96, 0x80000000, v165
	v_pk_add_f32 v[100:101], v[164:165], 0 neg_lo:[1,1] neg_hi:[1,1]
.LBB0_293:
	ds_read_b128 v[248:251], v136 offset:13312
	ds_read_b128 v[252:255], v136 offset:13376
	v_exp_f32_e32 v217, v116
	v_exp_f32_e32 v216, v104
	v_exp_f32_e32 v219, v117
	v_exp_f32_e32 v218, v105
	v_exp_f32_e32 v221, v118
	v_exp_f32_e32 v220, v106
	v_exp_f32_e32 v223, v119
	v_exp_f32_e32 v222, v107
	v_exp_f32_e32 v225, v124
	v_exp_f32_e32 v224, v108
	v_pk_add_f32 v[104:105], v[216:217], 0 op_sel_hi:[1,0]
	v_exp_f32_e32 v227, v125
	v_exp_f32_e32 v226, v109
	v_pk_add_f32 v[104:105], v[218:219], v[104:105]
	v_exp_f32_e32 v229, v126
	v_pk_add_f32 v[104:105], v[220:221], v[104:105]
	v_exp_f32_e32 v228, v110
	v_exp_f32_e32 v231, v127
	v_pk_add_f32 v[104:105], v[222:223], v[104:105]
	v_exp_f32_e32 v230, v111
	v_exp_f32_e32 v233, v128
	v_pk_add_f32 v[104:105], v[224:225], v[104:105]
	v_exp_f32_e32 v232, v112
	v_exp_f32_e32 v235, v129
	v_pk_add_f32 v[104:105], v[226:227], v[104:105]
	v_exp_f32_e32 v234, v113
	v_exp_f32_e32 v237, v130
	v_exp_f32_e32 v236, v114
	v_pk_add_f32 v[104:105], v[228:229], v[104:105]
	v_exp_f32_e32 v131, v131
	v_exp_f32_e32 v130, v115
	v_pk_add_f32 v[104:105], v[230:231], v[104:105]
	v_exp_f32_e32 v239, v132
	v_exp_f32_e32 v238, v120
	v_pk_add_f32 v[104:105], v[232:233], v[104:105]
	v_exp_f32_e32 v133, v133
	v_exp_f32_e32 v132, v121
	v_pk_add_f32 v[104:105], v[234:235], v[104:105]
	v_exp_f32_e32 v241, v134
	v_exp_f32_e32 v240, v122
	v_pk_add_f32 v[104:105], v[236:237], v[104:105]
	v_exp_f32_e32 v135, v135
	v_exp_f32_e32 v134, v123
	v_pk_add_f32 v[104:105], v[130:131], v[104:105]
	v_mov_b32_e32 v101, v100
	v_pk_add_f32 v[104:105], v[238:239], v[104:105]
	v_mov_b32_e32 v102, v100
	v_pk_add_f32 v[104:105], v[132:133], v[104:105]
	v_mov_b32_e32 v103, v100
	v_pk_add_f32 v[104:105], v[240:241], v[104:105]
	v_mov_b32_e32 v97, v96
	v_pk_add_f32 v[104:105], v[134:135], v[104:105]
	v_mov_b32_e32 v98, v96
	v_mov_b32_e32 v99, v96
	v_cvt_pk_bf16_f32 v116, v217, v219
	v_cvt_pk_bf16_f32 v117, v221, v223
	v_cvt_pk_bf16_f32 v118, v225, v227
	v_cvt_pk_bf16_f32 v119, v229, v231
	v_cvt_pk_bf16_f32 v124, v233, v235
	v_cvt_pk_bf16_f32 v125, v237, v131
	v_cvt_pk_bf16_f32 v126, v239, v133
	v_cvt_pk_bf16_f32 v127, v241, v135
	v_pk_add_f32 v[128:129], v[104:105], v[166:167]
	v_cvt_pk_bf16_f32 v104, v216, v218
	v_cvt_pk_bf16_f32 v105, v220, v222
	v_cvt_pk_bf16_f32 v106, v224, v226
	v_cvt_pk_bf16_f32 v107, v228, v230
	v_cvt_pk_bf16_f32 v108, v232, v234
	v_cvt_pk_bf16_f32 v109, v236, v130
	v_cvt_pk_bf16_f32 v110, v238, v132
	v_cvt_pk_bf16_f32 v111, v240, v134
	s_setprio 1
	ds_read_b128 v[216:219], v136 offset:15616
	ds_read_b128 v[220:223], v136 offset:15680
	ds_read_b128 v[224:227], v136 offset:17920
	ds_read_b128 v[228:231], v136 offset:17984
	ds_read_b128 v[232:235], v136 offset:20224
	ds_read_b128 v[236:239], v136 offset:20288
	s_waitcnt lgkmcnt(6)
	v_mfma_f32_16x16x32_bf16 v[92:95], v[248:251], v[116:119], v[92:95]
	v_mfma_f32_16x16x32_bf16 v[112:115], v[248:251], v[104:107], v[76:79]
	s_waitcnt lgkmcnt(6)
	v_mfma_f32_16x16x32_bf16 v[76:79], v[252:255], v[124:127], v[92:95]
	v_mfma_f32_16x16x32_bf16 v[92:95], v[252:255], v[108:111], v[112:115]
	s_waitcnt lgkmcnt(5)
	v_mfma_f32_16x16x32_bf16 v[88:91], v[216:219], v[116:119], v[88:91]
	v_mfma_f32_16x16x32_bf16 v[72:75], v[216:219], v[104:107], v[72:75]
	s_waitcnt lgkmcnt(4)
	v_mfma_f32_16x16x32_bf16 v[88:91], v[220:223], v[124:127], v[88:91]
	v_mfma_f32_16x16x32_bf16 v[72:75], v[220:223], v[108:111], v[72:75]
	s_waitcnt lgkmcnt(3)
	v_mfma_f32_16x16x32_bf16 v[84:87], v[224:227], v[116:119], v[84:87]
	v_mfma_f32_16x16x32_bf16 v[68:71], v[224:227], v[104:107], v[68:71]
	s_waitcnt lgkmcnt(2)
	v_mfma_f32_16x16x32_bf16 v[84:87], v[228:231], v[124:127], v[84:87]
	v_mfma_f32_16x16x32_bf16 v[68:71], v[228:231], v[108:111], v[68:71]
	s_waitcnt lgkmcnt(1)
	v_mfma_f32_16x16x32_bf16 v[64:67], v[232:235], v[104:107], v[64:67]
	v_mfma_f32_16x16x32_bf16 v[80:83], v[232:235], v[116:119], v[80:83]
	s_waitcnt lgkmcnt(0)
	v_mfma_f32_16x16x32_bf16 v[80:83], v[236:239], v[124:127], v[80:83]
	v_mfma_f32_16x16x32_bf16 v[64:67], v[236:239], v[108:111], v[64:67]
	s_setprio 0
	s_min_i32 s6, s1, s4
	s_lshl_b32 s7, s6, 6
	s_add_i32 s7, s7, s16
	s_waitcnt vmcnt(8)
	ds_write_b128 v208, v[0:3] offset:22528
	s_waitcnt vmcnt(7)
	ds_write_b128 v209, v[4:7] offset:22528
	s_waitcnt vmcnt(7)
	ds_write_b128 v210, v[36:39] offset:22528
	s_waitcnt vmcnt(6)
	ds_write_b64 v211, v[40:41] offset:35840
	ds_write_b64 v212, v[42:43] offset:35840
	s_waitcnt vmcnt(5)
	ds_write_b64 v213, v[32:33] offset:35840
	ds_write_b64 v214, v[34:35] offset:35840
	v_add_u32_e32 v32, s7, v205
	v_add_u32_e32 v0, s7, v203
	v_add_u32_e32 v4, s7, v204
	v_ashrrev_i32_e32 v33, 31, v32
	v_ashrrev_i32_e32 v1, 31, v0
	v_ashrrev_i32_e32 v5, 31, v4
	v_lshlrev_b64 v[34:35], 9, v[32:33]
	v_lshlrev_b64 v[32:33], 6, v[32:33]
	v_lshlrev_b64 v[2:3], 9, v[0:1]
	v_lshlrev_b64 v[0:1], 6, v[0:1]
	v_lshlrev_b64 v[6:7], 9, v[4:5]
	v_lshlrev_b64 v[4:5], 6, v[4:5]
	v_lshl_add_u64 v[32:33], v[160:161], 0, v[32:33]
	v_lshl_add_u64 v[0:1], v[152:153], 0, v[0:1]
	v_lshl_add_u64 v[4:5], v[156:157], 0, v[4:5]
	v_lshl_add_u64 v[34:35], v[162:163], 0, v[34:35]
	v_lshl_add_u64 v[32:33], v[32:33], 0, s[18:19]
	v_lshl_add_u64 v[2:3], v[154:155], 0, v[2:3]
	v_lshl_add_u64 v[0:1], v[0:1], 0, s[18:19]
	v_lshl_add_u64 v[6:7], v[158:159], 0, v[6:7]
	v_lshl_add_u64 v[4:5], v[4:5], 0, s[18:19]
	v_cndmask_b32_e64 v33, v33, v35, s[42:43]
	v_cndmask_b32_e64 v32, v32, v34, s[42:43]
	s_lshl_b32 s94, s6, 7
	s_waitcnt lgkmcnt(0)
	s_barrier
	v_cndmask_b32_e64 v1, v1, v3, s[38:39]
	v_cndmask_b32_e64 v0, v0, v2, s[38:39]
	v_cndmask_b32_e64 v5, v5, v7, s[40:41]
	v_cndmask_b32_e64 v4, v4, v6, s[40:41]
	global_load_dwordx4 v[36:39], v[32:33], off
	v_lshl_add_u64 v[32:33], v[146:147], 0, s[94:95]
	v_lshl_add_u64 v[34:35], v[148:149], 0, s[94:95]
	global_load_dwordx4 v[0:3], v[0:1], off
	s_nop 0
	global_load_dwordx4 v[4:7], v[4:5], off
	s_nop 0
	global_load_dwordx4 v[40:43], v[32:33], off
	s_nop 0
	global_load_dwordx4 v[32:35], v[34:35], off
	s_setprio 1
	ds_read_b128 v[104:107], v151 offset:22528
	ds_read_b128 v[112:115], v151 offset:22592
	s_waitcnt lgkmcnt(1)
	v_mfma_f32_16x16x32_bf16 v[108:111], v[104:107], v[8:11], v[96:99]
	ds_read_b128 v[120:123], v151 offset:25920
	ds_read_b128 v[124:127], v151 offset:25984
	ds_read_b128 v[130:133], v151 offset:29248
	v_mfma_f32_16x16x32_bf16 v[104:107], v[104:107], v[20:23], v[100:103]
	ds_read_b128 v[216:219], v151 offset:32640
	s_waitcnt lgkmcnt(4)
	v_mfma_f32_16x16x32_bf16 v[108:111], v[112:115], v[12:15], v[108:111]
	v_mfma_f32_16x16x32_bf16 v[104:107], v[112:115], v[24:27], v[104:107]
	ds_read_b128 v[112:115], v151 offset:22656
	s_waitcnt lgkmcnt(0)
	v_mfma_f32_16x16x32_bf16 v[116:119], v[112:115], v[16:19], v[108:111]
	s_nop 3
	ds_read_b128 v[108:111], v151 offset:25856
	v_mfma_f32_16x16x32_bf16 v[104:107], v[112:115], v[28:31], v[104:107]
	s_waitcnt lgkmcnt(0)
	v_mfma_f32_16x16x32_bf16 v[112:115], v[108:111], v[8:11], v[96:99]
	v_mfma_f32_16x16x32_bf16 v[108:111], v[108:111], v[20:23], v[100:103]
	v_mfma_f32_16x16x32_bf16 v[112:115], v[120:123], v[12:15], v[112:115]
	v_mfma_f32_16x16x32_bf16 v[108:111], v[120:123], v[24:27], v[108:111]
	v_mfma_f32_16x16x32_bf16 v[120:123], v[124:127], v[16:19], v[112:115]
	v_mfma_f32_16x16x32_bf16 v[112:115], v[124:127], v[28:31], v[108:111]
	s_nop 5
	ds_read_b128 v[108:111], v151 offset:29184
	s_waitcnt lgkmcnt(0)
	v_mfma_f32_16x16x32_bf16 v[124:127], v[108:111], v[8:11], v[96:99]
	v_mfma_f32_16x16x32_bf16 v[108:111], v[108:111], v[20:23], v[100:103]
	v_mfma_f32_16x16x32_bf16 v[124:127], v[130:133], v[12:15], v[124:127]
	v_mfma_f32_16x16x32_bf16 v[108:111], v[130:133], v[24:27], v[108:111]
	ds_read_b128 v[130:133], v151 offset:29312
	s_waitcnt lgkmcnt(0)
	v_mfma_f32_16x16x32_bf16 v[124:127], v[130:133], v[16:19], v[124:127]
	v_mfma_f32_16x16x32_bf16 v[108:111], v[130:133], v[28:31], v[108:111]
	ds_read_b128 v[130:133], v151 offset:32512
	s_waitcnt lgkmcnt(0)
	v_mfma_f32_16x16x32_bf16 v[96:99], v[130:133], v[8:11], v[96:99]
	v_mfma_f32_16x16x32_bf16 v[100:103], v[130:133], v[20:23], v[100:103]
	ds_read_b128 v[130:133], v151 offset:32576
	s_waitcnt lgkmcnt(0)
	v_mfma_f32_16x16x32_bf16 v[96:99], v[130:133], v[12:15], v[96:99]
	v_mfma_f32_16x16x32_bf16 v[130:133], v[130:133], v[24:27], v[100:103]
	v_mfma_f32_16x16x32_bf16 v[100:103], v[216:219], v[16:19], v[96:99]
	v_mfma_f32_16x16x32_bf16 v[96:99], v[216:219], v[28:31], v[130:133]
	s_setprio 0
	s_nop 4
	v_max_f32_e32 v130, v117, v117
	v_max_f32_e32 v131, v116, v116
	v_max_f32_e32 v130, v131, v130
	v_max_f32_e32 v131, v119, v119
	v_max_f32_e32 v132, v118, v118
	v_max_f32_e32 v131, v132, v131
	v_max_f32_e32 v132, v123, v123
	v_max_f32_e32 v133, v122, v122
	v_max_f32_e32 v132, v133, v132
	v_max3_f32 v132, v120, v121, v132
	v_max3_f32 v130, v130, v131, v132
	v_max_f32_e32 v131, v127, v127
	v_max_f32_e32 v132, v126, v126
	v_max_f32_e32 v131, v132, v131
	v_max_f32_e32 v132, v103, v103
	v_max_f32_e32 v133, v102, v102
	v_max_f32_e32 v132, v133, v132
	v_max3_f32 v131, v124, v125, v131
	v_max3_f32 v132, v100, v101, v132
	v_max3_f32 v130, v130, v131, v132
	v_mov_b32_e32 v131, v130
	v_max_f32_e32 v132, v104, v104
	v_max_f32_e32 v133, v106, v106
	v_max_f32_e32 v134, v114, v114
	s_mov_b32 s6, 0x41000000
	s_nop 1
	v_permlane16_swap_b32_e32 v131, v130
	v_max_f32_e32 v130, v130, v131
	v_mov_b32_e32 v131, v130
	s_nop 1
	v_permlane32_swap_b32_e32 v131, v130
	v_max_f32_e32 v130, v130, v131
	v_max_f32_e32 v131, v105, v105
	v_max_f32_e32 v131, v132, v131
	v_max_f32_e32 v132, v107, v107
	v_max_f32_e32 v132, v133, v132
	v_max_f32_e32 v133, v115, v115
	v_max_f32_e32 v133, v134, v133
	v_max3_f32 v133, v112, v113, v133
	v_max3_f32 v131, v131, v132, v133
	v_max_f32_e32 v132, v111, v111
	v_max_f32_e32 v133, v110, v110
	v_max_f32_e32 v132, v133, v132
	v_max_f32_e32 v133, v99, v99
	v_max_f32_e32 v134, v98, v98
	v_max_f32_e32 v133, v134, v133
	v_max3_f32 v132, v108, v109, v132
	v_max3_f32 v133, v96, v97, v133
	v_max3_f32 v131, v131, v132, v133
	v_mov_b32_e32 v132, v131
	s_nop 1
	v_permlane16_swap_b32_e32 v132, v131
	v_max_f32_e32 v131, v131, v132
	v_mov_b32_e32 v132, v131
	s_nop 1
	v_permlane32_swap_b32_e32 v132, v131
	v_max_f32_e32 v131, v131, v132
	v_max_f32_e32 v132, v130, v131
	v_cmp_lt_f32_e32 vcc, s6, v132
	s_cbranch_vccz .LBB0_290
	v_max_f32_e32 v130, v130, v130
	v_max_f32_e32 v130, 0, v130
	v_pk_add_f32 v[116:117], v[116:117], v[130:131] op_sel_hi:[1,0] neg_lo:[0,1] neg_hi:[0,1]
	v_pk_add_f32 v[118:119], v[118:119], v[130:131] op_sel_hi:[1,0] neg_lo:[0,1] neg_hi:[0,1]
	v_pk_add_f32 v[120:121], v[120:121], v[130:131] op_sel_hi:[1,0] neg_lo:[0,1] neg_hi:[0,1]
	v_pk_add_f32 v[122:123], v[122:123], v[130:131] op_sel_hi:[1,0] neg_lo:[0,1] neg_hi:[0,1]
	v_pk_add_f32 v[124:125], v[124:125], v[130:131] op_sel_hi:[1,0] neg_lo:[0,1] neg_hi:[0,1]
	v_pk_add_f32 v[126:127], v[126:127], v[130:131] op_sel_hi:[1,0] neg_lo:[0,1] neg_hi:[0,1]
	v_pk_add_f32 v[100:101], v[100:101], v[130:131] op_sel_hi:[1,0] neg_lo:[0,1] neg_hi:[0,1]
	v_pk_add_f32 v[102:103], v[102:103], v[130:131] op_sel_hi:[1,0] neg_lo:[0,1] neg_hi:[0,1]
	v_max_f32_e32 v131, v131, v131
	v_exp_f32_e64 v132, -v130
	v_max_f32_e32 v134, 0, v131
	v_exp_f32_e64 v166, -v134
	v_mov_b32_e32 v135, v130
	v_mov_b32_e32 v167, v132
	v_pk_mul_f32 v[78:79], v[78:79], v[132:133] op_sel_hi:[1,0]
	v_pk_mul_f32 v[76:77], v[76:77], v[132:133] op_sel_hi:[1,0]
	v_pk_mul_f32 v[90:91], v[90:91], v[132:133] op_sel_hi:[1,0]
	v_pk_mul_f32 v[88:89], v[88:89], v[132:133] op_sel_hi:[1,0]
	v_pk_mul_f32 v[86:87], v[86:87], v[132:133] op_sel_hi:[1,0]
	v_pk_mul_f32 v[84:85], v[84:85], v[132:133] op_sel_hi:[1,0]
	v_pk_mul_f32 v[82:83], v[82:83], v[132:133] op_sel_hi:[1,0]
	v_pk_mul_f32 v[80:81], v[80:81], v[132:133] op_sel_hi:[1,0]
	v_pk_add_f32 v[164:165], v[164:165], v[134:135]
	v_pk_mul_f32 v[128:129], v[128:129], v[166:167]
	v_pk_mul_f32 v[94:95], v[94:95], v[166:167] op_sel_hi:[1,0]
	v_pk_mul_f32 v[92:93], v[92:93], v[166:167] op_sel_hi:[1,0]
	v_pk_mul_f32 v[74:75], v[74:75], v[166:167] op_sel_hi:[1,0]
	v_pk_mul_f32 v[72:73], v[72:73], v[166:167] op_sel_hi:[1,0]
	v_pk_mul_f32 v[70:71], v[70:71], v[166:167] op_sel_hi:[1,0]
	v_pk_mul_f32 v[68:69], v[68:69], v[166:167] op_sel_hi:[1,0]
	v_pk_mul_f32 v[66:67], v[66:67], v[166:167] op_sel_hi:[1,0]
	v_pk_mul_f32 v[64:65], v[64:65], v[166:167] op_sel_hi:[1,0]
	v_pk_add_f32 v[104:105], v[104:105], v[134:135] op_sel_hi:[1,0] neg_lo:[0,1] neg_hi:[0,1]
	v_pk_add_f32 v[106:107], v[106:107], v[134:135] op_sel_hi:[1,0] neg_lo:[0,1] neg_hi:[0,1]
	v_pk_add_f32 v[112:113], v[112:113], v[134:135] op_sel_hi:[1,0] neg_lo:[0,1] neg_hi:[0,1]
	v_pk_add_f32 v[114:115], v[114:115], v[134:135] op_sel_hi:[1,0] neg_lo:[0,1] neg_hi:[0,1]
	v_pk_add_f32 v[108:109], v[108:109], v[134:135] op_sel_hi:[1,0] neg_lo:[0,1] neg_hi:[0,1]
	v_pk_add_f32 v[110:111], v[110:111], v[134:135] op_sel_hi:[1,0] neg_lo:[0,1] neg_hi:[0,1]
	v_pk_add_f32 v[96:97], v[96:97], v[134:135] op_sel_hi:[1,0] neg_lo:[0,1] neg_hi:[0,1]
	v_pk_add_f32 v[98:99], v[98:99], v[134:135] op_sel_hi:[1,0] neg_lo:[0,1] neg_hi:[0,1]
	s_branch .LBB0_290
